# GEMM kinds 0,2,3: half of the workgroups (blockIdx bit 3) start the unit loop 2.2us later so epilogue store bursts of the two halves interleave with the other half's K loop
# speedup vs baseline: 1.0035x; 1.0035x over previous
; #define LAS __attribute__((address_space(3)))
; #define TIDX tid_opaque()
; __device__ __forceinline__ void run_gemm(unsigned char* smem, const GDesc& d) {
;     pg8::Gemm g; g.A = d.A; g.Bt = d.Bt; g.M = d.M; g.N = d.N; g.K = d.K;
;     pg8::StaticOrder S; S.init(d.M, d.N, (int)gridDim.x, (int)blockIdx.x);
;     EpiAny E; E.d = d;
;     if (d.kind == 0 || d.kind == 2 || d.kind == 3) {
;         const float* part = (const float*)d.q3; float* rtab = (float*)(smem + RT_OFF); int* pmtab = (int*)(smem + RT_OFF + 12 * 1024); const int tid = TIDX;
;         if (tid < 16) { pg8::Unit u; pmtab[tid] = S.next(tid, u) ? u.pm : -1; }
;         __syncthreads();
; #pragma unroll
;         for (int k = 0; k < 6; ++k) { const int idx = tid + 512 * k, i = idx >> 8, row = idx & 255; const int pm = (i < 12) ? pmtab[i] : -1;
;             if (pm >= 0) { const f32x4* pp = (const f32x4*)(part + (size_t)(pm * BM + row) * 16); const f32x4 a = pp[0], b = pp[1], c = pp[2], e4 = pp[3];
;                 const float ss = ((a[0] + a[1]) + (a[2] + a[3])) + ((b[0] + b[1]) + (b[2] + b[3])) + ((c[0] + c[1]) + (c[2] + c[3])) + ((e4[0] + e4[1]) + (e4[2] + e4[3]));
;                 rtab[idx] = 1.0f / sqrtf(ss * (1.0f / DM) + 1e-6f); } }
;         __syncthreads();
;     }
;     pg8::gemm_phase<EpiAny>((LAS unsigned char*)smem, g, S, E, !(d.kind == 0 || d.kind == 7));
.LBB0_442:
	s_bitcmp1_b32 s2, 3
	s_cbranch_scc0 .Lstag_done
	s_mov_b32 s99, 0
	s_cmp_eq_u32 s5, 0
	s_cselect_b32 s99, 220, s99
	s_cmp_eq_u32 s5, 2
	s_cselect_b32 s99, 220, s99
	s_cmp_eq_u32 s5, 3
	s_cselect_b32 s99, 220, s99
	s_cmp_eq_u32 s99, 0
	s_cbranch_scc1 .Lstag_done
	s_memrealtime s[100:101]
	s_waitcnt lgkmcnt(0)
	s_mov_b32 s98, s100
.Lstag_loop:
	s_sleep 8
	s_memrealtime s[100:101]
	s_waitcnt lgkmcnt(0)
	s_sub_u32 s100, s100, s98
	s_cmp_lt_u32 s100, s99
	s_cbranch_scc1 .Lstag_loop
